# MERGE keep-epilogue (segments 0,1): gate-tile loads of batch k+1 prefetched into free registers under batch k's compute (epilogue de-serialisation)
# speedup vs baseline: 1.0026x; 1.0026x over previous
;     __device__ __forceinline__ void operator()(f32x4 (&acc)[2][2][4][2], const Unit& u, int wr, int wc, int fr, int fq) const {
;     ...
;         } else if (u.seg < 2) {
;             const bf16_t* gbase = gl + (size_t)u.seg * 8 * 65536;
; #pragma unroll
;             for (int am = 0; am < 4; ++am) { const int ai = am >> 1, mb = (am & 1) * 2;
;                 u32x4 ra[2][2], rb[2][2];
; #pragma unroll
;                 for (int mm = 0; mm < 2; ++mm)
; #pragma unroll
;                     for (int bj = 0; bj < 2; ++bj) { const bf16_t* gp = gbase + ((ai * 4 + mb + mm) * 2 + bj) * 512; ra[mm][bj] = *(const u32x4*)gp; rb[mm][bj] = *(const u32x4*)(gp + 8 * 65536); }
; #pragma unroll
;                 for (int mm = 0; mm < 2; ++mm)
; #pragma unroll
;                     for (int bj = 0; bj < 2; ++bj) { const int m = mb + mm; float ga[8], gb[8]; unpack8(ra[mm][bj], ga); unpack8(rb[mm][bj], gb);
;                         f32x4 v0 = acc[ai][bj][m][0], v1 = acc[ai][bj][m][1];
;                         v0[0] *= ga[0] * __builtin_amdgcn_rcpf(gb[0]); v0[1] *= ga[1] * __builtin_amdgcn_rcpf(gb[1]); v0[2] *= ga[2] * __builtin_amdgcn_rcpf(gb[2]); v0[3] *= ga[3] * __builtin_amdgcn_rcpf(gb[3]);
;                         v1[0] *= ga[4] * __builtin_amdgcn_rcpf(gb[4]); v1[1] *= ga[5] * __builtin_amdgcn_rcpf(gb[5]); v1[2] *= ga[6] * __builtin_amdgcn_rcpf(gb[6]); v1[3] *= ga[7] * __builtin_amdgcn_rcpf(gb[7]);
;                         acc[ai][bj][m][0] = v0; acc[ai][bj][m][1] = v1; }
;             }
.LBB0_883:
	s_andn2_b64 vcc, exec, s[12:13]
	s_cbranch_vccnz .LBB0_885
	s_ashr_i32 s23, s22, 31
	s_lshl_b64 s[6:7], s[22:23], 20
	v_lshl_add_u64 v[158:159], v[192:193], 0, s[6:7]
	global_load_dwordx4 v[130:133], v[158:159], off
	v_add_co_u32_e32 v160, vcc, 0x100000, v158
	s_movk_i32 s1, 0x2000
	s_nop 0
	v_addc_co_u32_e32 v161, vcc, 0, v159, vcc
	global_load_dwordx4 v[134:137], v[160:161], off
	global_load_dwordx4 v[138:141], v[158:159], off offset:1024
	global_load_dwordx4 v[142:145], v[160:161], off offset:1024
	global_load_dwordx4 v[146:149], v[158:159], off offset:2048
	global_load_dwordx4 v[150:153], v[160:161], off offset:2048
	global_load_dwordx4 v[154:157], v[158:159], off offset:3072
	s_nop 0
	global_load_dwordx4 v[160:163], v[160:161], off offset:3072
	s_mov_b32 s98, 0x1000
	s_mov_b32 s99, 0
	v_lshl_add_u64 v[242:243], v[158:159], 0, s[98:99]
	s_mov_b32 s98, 0x101000
	v_lshl_add_u64 v[252:253], v[158:159], 0, s[98:99]
	global_load_dwordx4 v[228:231], v[242:243], off
	global_load_dwordx4 v[232:235], v[252:253], off
	global_load_dwordx4 v[236:239], v[242:243], off offset:1024
	global_load_dwordx4 v[244:247], v[252:253], off offset:1024
	global_load_dwordx4 v[248:251], v[242:243], off offset:2048
	global_load_dwordx4 v[198:201], v[252:253], off offset:2048
	global_load_dwordx4 v[212:215], v[242:243], off offset:3072
	global_load_dwordx4 v[216:219], v[252:253], off offset:3072
	s_waitcnt vmcnt(8)
	v_lshlrev_b32_e32 v1, 16, v134
	v_and_b32_e32 v164, 0xffff0000, v134
	v_lshlrev_b32_e32 v165, 16, v135
	v_and_b32_e32 v182, 0xffff0000, v135
	v_rcp_f32_e32 v134, v1
	v_rcp_f32_e32 v135, v164
	v_lshlrev_b32_e32 v183, 16, v136
	v_and_b32_e32 v184, 0xffff0000, v136
	v_lshlrev_b32_e32 v185, 16, v137
	v_and_b32_e32 v192, 0xffff0000, v137
	v_lshlrev_b32_e32 v136, 16, v130
	v_and_b32_e32 v137, 0xffff0000, v130
	v_pk_mul_f32 v[134:135], v[134:135], v[136:137]
	v_lshlrev_b32_e32 v130, 16, v131
	v_pk_mul_f32 v[126:127], v[126:127], v[134:135]
	v_rcp_f32_e32 v134, v165
	v_rcp_f32_e32 v135, v182
	v_and_b32_e32 v131, 0xffff0000, v131
	v_lshlrev_b32_e32 v1, 16, v142
	v_lshlrev_b32_e32 v136, 16, v144
	v_pk_mul_f32 v[130:131], v[134:135], v[130:131]
	v_lshlrev_b32_e32 v134, 16, v132
	v_pk_mul_f32 v[128:129], v[128:129], v[130:131]
	v_rcp_f32_e32 v130, v183
	v_rcp_f32_e32 v131, v184
	v_and_b32_e32 v135, 0xffff0000, v132
	v_lshlrev_b32_e32 v132, 16, v133
	v_and_b32_e32 v133, 0xffff0000, v133
	v_pk_mul_f32 v[130:131], v[130:131], v[134:135]
	v_lshlrev_b32_e32 v134, 16, v143
	v_pk_mul_f32 v[122:123], v[122:123], v[130:131]
	v_rcp_f32_e32 v130, v185
	v_rcp_f32_e32 v131, v192
	v_and_b32_e32 v135, 0xffff0000, v143
	v_and_b32_e32 v137, 0xffff0000, v144
	v_and_b32_e32 v143, 0xffff0000, v145
	v_pk_mul_f32 v[130:131], v[130:131], v[132:133]
	v_lshlrev_b32_e32 v132, 16, v138
	v_pk_mul_f32 v[124:125], v[124:125], v[130:131]
	v_and_b32_e32 v131, 0xffff0000, v142
	v_rcp_f32_e32 v130, v1
	v_rcp_f32_e32 v131, v131
	v_and_b32_e32 v133, 0xffff0000, v138
	v_lshlrev_b32_e32 v142, 16, v145
	v_lshlrev_b32_e32 v1, 16, v150
	v_pk_mul_f32 v[130:131], v[130:131], v[132:133]
	v_lshlrev_b32_e32 v132, 16, v139
	v_pk_mul_f32 v[94:95], v[94:95], v[130:131]
	v_rcp_f32_e32 v130, v134
	v_rcp_f32_e32 v131, v135
	v_and_b32_e32 v133, 0xffff0000, v139
	v_lshlrev_b32_e32 v134, 16, v151
	v_and_b32_e32 v135, 0xffff0000, v151
	v_pk_mul_f32 v[130:131], v[130:131], v[132:133]
	v_lshlrev_b32_e32 v132, 16, v140
	v_pk_mul_f32 v[96:97], v[96:97], v[130:131]
	v_rcp_f32_e32 v130, v136
	v_rcp_f32_e32 v131, v137
	v_and_b32_e32 v133, 0xffff0000, v140
	v_lshlrev_b32_e32 v136, 16, v152
	v_and_b32_e32 v137, 0xffff0000, v152
	v_pk_mul_f32 v[130:131], v[130:131], v[132:133]
	v_lshlrev_b32_e32 v132, 16, v141
	v_pk_mul_f32 v[90:91], v[90:91], v[130:131]
	v_rcp_f32_e32 v130, v142
	v_rcp_f32_e32 v131, v143
	v_and_b32_e32 v133, 0xffff0000, v141
	v_lshlrev_b32_e32 v138, 16, v153
	v_and_b32_e32 v139, 0xffff0000, v153
	v_pk_mul_f32 v[130:131], v[130:131], v[132:133]
	v_lshlrev_b32_e32 v132, 16, v146
	v_pk_mul_f32 v[92:93], v[92:93], v[130:131]
	v_and_b32_e32 v131, 0xffff0000, v150
	v_rcp_f32_e32 v130, v1
	v_rcp_f32_e32 v131, v131
	v_and_b32_e32 v133, 0xffff0000, v146
	v_lshlrev_b32_e32 v1, 16, v160
	v_add_co_u32_e32 v146, vcc, s48, v158
	v_pk_mul_f32 v[130:131], v[130:131], v[132:133]
	v_lshlrev_b32_e32 v132, 16, v147
	v_pk_mul_f32 v[118:119], v[118:119], v[130:131]
	v_rcp_f32_e32 v130, v134
	v_rcp_f32_e32 v131, v135
	v_and_b32_e32 v133, 0xffff0000, v147
	v_lshlrev_b32_e32 v134, 16, v161
	v_and_b32_e32 v135, 0xffff0000, v161
	v_pk_mul_f32 v[130:131], v[130:131], v[132:133]
	v_lshlrev_b32_e32 v132, 16, v148
	v_pk_mul_f32 v[120:121], v[120:121], v[130:131]
	v_rcp_f32_e32 v130, v136
	v_rcp_f32_e32 v131, v137
	v_and_b32_e32 v133, 0xffff0000, v148
	v_lshlrev_b32_e32 v136, 16, v162
	v_and_b32_e32 v137, 0xffff0000, v162
	v_pk_mul_f32 v[130:131], v[130:131], v[132:133]
	v_lshlrev_b32_e32 v132, 16, v149
	v_pk_mul_f32 v[114:115], v[114:115], v[130:131]
	v_rcp_f32_e32 v130, v138
	v_rcp_f32_e32 v131, v139
	v_and_b32_e32 v133, 0xffff0000, v149
	v_lshlrev_b32_e32 v138, 16, v163
	v_and_b32_e32 v139, 0xffff0000, v163
	v_pk_mul_f32 v[130:131], v[130:131], v[132:133]
	v_lshlrev_b32_e32 v132, 16, v154
	v_pk_mul_f32 v[116:117], v[116:117], v[130:131]
	v_and_b32_e32 v131, 0xffff0000, v160
	v_rcp_f32_e32 v130, v1
	v_rcp_f32_e32 v131, v131
	v_and_b32_e32 v133, 0xffff0000, v154
	v_addc_co_u32_e32 v147, vcc, 0, v159, vcc
	v_pk_mul_f32 v[130:131], v[130:131], v[132:133]
	v_lshlrev_b32_e32 v132, 16, v155
	v_pk_mul_f32 v[86:87], v[86:87], v[130:131]
	v_rcp_f32_e32 v130, v134
	v_rcp_f32_e32 v131, v135
	v_and_b32_e32 v133, 0xffff0000, v155
	v_add_co_u32_e32 v154, vcc, s1, v158
	v_pk_mul_f32 v[130:131], v[130:131], v[132:133]
	v_lshlrev_b32_e32 v132, 16, v156
	v_pk_mul_f32 v[88:89], v[88:89], v[130:131]
	v_rcp_f32_e32 v130, v136
	v_rcp_f32_e32 v131, v137
	v_and_b32_e32 v133, 0xffff0000, v156
	v_addc_co_u32_e32 v155, vcc, 0, v159, vcc
	v_pk_mul_f32 v[130:131], v[130:131], v[132:133]
	s_mov_b32 s1, 0x101000
	v_pk_mul_f32 v[82:83], v[82:83], v[130:131]
	v_rcp_f32_e32 v130, v138
	v_rcp_f32_e32 v131, v139
	v_lshlrev_b32_e32 v132, 16, v157
	v_and_b32_e32 v133, 0xffff0000, v157
	v_add_co_u32_e32 v148, vcc, s1, v158
	v_pk_mul_f32 v[130:131], v[130:131], v[132:133]
	s_nop 0
	v_addc_co_u32_e32 v149, vcc, 0, v159, vcc
	s_mov_b32 s1, 0x102000
	v_pk_mul_f32 v[84:85], v[84:85], v[130:131]
	s_waitcnt vmcnt(0)
;     __device__ __forceinline__ void operator()(f32x4 (&acc)[2][2][4][2], const Unit& u, int wr, int wc, int fr, int fq) const {
;     ...
;         } else if (u.seg < 2) {
;             const bf16_t* gbase = gl + (size_t)u.seg * 8 * 65536;
; #pragma unroll
;             for (int am = 0; am < 4; ++am) { const int ai = am >> 1, mb = (am & 1) * 2;
;                 u32x4 ra[2][2], rb[2][2];
; #pragma unroll
;                 for (int mm = 0; mm < 2; ++mm)
; #pragma unroll
;                     for (int bj = 0; bj < 2; ++bj) { const bf16_t* gp = gbase + ((ai * 4 + mb + mm) * 2 + bj) * 512; ra[mm][bj] = *(const u32x4*)gp; rb[mm][bj] = *(const u32x4*)(gp + 8 * 65536); }
; #pragma unroll
;                 for (int mm = 0; mm < 2; ++mm)
; #pragma unroll
;                     for (int bj = 0; bj < 2; ++bj) { const int m = mb + mm; float ga[8], gb[8]; unpack8(ra[mm][bj], ga); unpack8(rb[mm][bj], gb);
;                         f32x4 v0 = acc[ai][bj][m][0], v1 = acc[ai][bj][m][1];
;                         v0[0] *= ga[0] * __builtin_amdgcn_rcpf(gb[0]); v0[1] *= ga[1] * __builtin_amdgcn_rcpf(gb[1]); v0[2] *= ga[2] * __builtin_amdgcn_rcpf(gb[2]); v0[3] *= ga[3] * __builtin_amdgcn_rcpf(gb[3]);
;                         v1[0] *= ga[4] * __builtin_amdgcn_rcpf(gb[4]); v1[1] *= ga[5] * __builtin_amdgcn_rcpf(gb[5]); v1[2] *= ga[6] * __builtin_amdgcn_rcpf(gb[6]); v1[3] *= ga[7] * __builtin_amdgcn_rcpf(gb[7]);
;                         acc[ai][bj][m][0] = v0; acc[ai][bj][m][1] = v1; }
;             }
	v_mov_b64_e32 v[130:131], v[228:229]
	v_mov_b64_e32 v[132:133], v[230:231]
	v_add_co_u32_e32 v160, vcc, s1, v158
	s_movk_i32 s1, 0x3000
	s_nop 0
	v_addc_co_u32_e32 v161, vcc, 0, v159, vcc
	v_mov_b64_e32 v[138:139], v[232:233]
	v_mov_b64_e32 v[140:141], v[234:235]
	v_mov_b64_e32 v[134:135], v[236:237]
	v_mov_b64_e32 v[136:137], v[238:239]
	v_mov_b64_e32 v[150:151], v[244:245]
	v_mov_b64_e32 v[152:153], v[246:247]
	v_mov_b64_e32 v[142:143], v[248:249]
	v_mov_b64_e32 v[144:145], v[250:251]
	v_mov_b64_e32 v[162:163], v[198:199]
	v_mov_b64_e32 v[164:165], v[200:201]
	v_mov_b64_e32 v[182:183], v[212:213]
	v_mov_b64_e32 v[184:185], v[214:215]
	s_nop 0
	v_mov_b64_e32 v[146:147], v[216:217]
	v_mov_b64_e32 v[148:149], v[218:219]
	s_mov_b32 s98, 0x2000
	s_mov_b32 s99, 0
	v_lshl_add_u64 v[242:243], v[158:159], 0, s[98:99]
	s_mov_b32 s98, 0x102000
	v_lshl_add_u64 v[252:253], v[158:159], 0, s[98:99]
	global_load_dwordx4 v[228:231], v[242:243], off
	global_load_dwordx4 v[232:235], v[252:253], off
	global_load_dwordx4 v[236:239], v[242:243], off offset:1024
	global_load_dwordx4 v[244:247], v[252:253], off offset:1024
	global_load_dwordx4 v[248:251], v[242:243], off offset:2048
	global_load_dwordx4 v[198:201], v[252:253], off offset:2048
	global_load_dwordx4 v[212:215], v[242:243], off offset:3072
	global_load_dwordx4 v[216:219], v[252:253], off offset:3072
	v_lshlrev_b32_e32 v1, 16, v138
	v_and_b32_e32 v156, 0xffff0000, v138
	v_lshlrev_b32_e32 v157, 16, v139
	v_and_b32_e32 v192, 0xffff0000, v139
	v_rcp_f32_e32 v138, v1
	v_rcp_f32_e32 v139, v156
	v_lshlrev_b32_e32 v193, 16, v140
	v_and_b32_e32 v194, 0xffff0000, v140
	v_lshlrev_b32_e32 v195, 16, v141
	v_and_b32_e32 v196, 0xffff0000, v141
	v_lshlrev_b32_e32 v140, 16, v130
	v_and_b32_e32 v141, 0xffff0000, v130
	v_pk_mul_f32 v[138:139], v[138:139], v[140:141]
	v_lshlrev_b32_e32 v130, 16, v131
	v_pk_mul_f32 v[110:111], v[110:111], v[138:139]
	v_rcp_f32_e32 v138, v157
	v_rcp_f32_e32 v139, v192
	v_and_b32_e32 v131, 0xffff0000, v131
	v_lshlrev_b32_e32 v1, 16, v150
	v_lshlrev_b32_e32 v140, 16, v152
	v_pk_mul_f32 v[130:131], v[138:139], v[130:131]
	v_lshlrev_b32_e32 v138, 16, v132
	v_pk_mul_f32 v[112:113], v[112:113], v[130:131]
	v_rcp_f32_e32 v130, v193
	v_rcp_f32_e32 v131, v194
	v_and_b32_e32 v139, 0xffff0000, v132
	v_lshlrev_b32_e32 v132, 16, v133
	v_and_b32_e32 v133, 0xffff0000, v133
	v_pk_mul_f32 v[130:131], v[130:131], v[138:139]
	v_lshlrev_b32_e32 v138, 16, v151
	v_pk_mul_f32 v[106:107], v[106:107], v[130:131]
	v_rcp_f32_e32 v130, v195
	v_rcp_f32_e32 v131, v196
	v_and_b32_e32 v139, 0xffff0000, v151
	v_and_b32_e32 v141, 0xffff0000, v152
	v_and_b32_e32 v151, 0xffff0000, v153
	v_pk_mul_f32 v[130:131], v[130:131], v[132:133]
	v_lshlrev_b32_e32 v132, 16, v134
	v_pk_mul_f32 v[108:109], v[108:109], v[130:131]
	v_and_b32_e32 v131, 0xffff0000, v150
	v_rcp_f32_e32 v130, v1
	v_rcp_f32_e32 v131, v131
	v_and_b32_e32 v133, 0xffff0000, v134
	v_lshlrev_b32_e32 v150, 16, v153
	v_lshlrev_b32_e32 v1, 16, v162
	v_pk_mul_f32 v[130:131], v[130:131], v[132:133]
	v_lshlrev_b32_e32 v132, 16, v135
	v_pk_mul_f32 v[78:79], v[78:79], v[130:131]
	v_rcp_f32_e32 v130, v138
	v_rcp_f32_e32 v131, v139
	v_and_b32_e32 v133, 0xffff0000, v135
	v_lshlrev_b32_e32 v134, 16, v163
	v_and_b32_e32 v135, 0xffff0000, v163
	v_pk_mul_f32 v[130:131], v[130:131], v[132:133]
	v_lshlrev_b32_e32 v132, 16, v136
	v_pk_mul_f32 v[80:81], v[80:81], v[130:131]
	v_rcp_f32_e32 v130, v140
	v_rcp_f32_e32 v131, v141
	v_and_b32_e32 v133, 0xffff0000, v136
	v_lshlrev_b32_e32 v136, 16, v164
	v_lshlrev_b32_e32 v138, 16, v165
	v_pk_mul_f32 v[130:131], v[130:131], v[132:133]
	v_lshlrev_b32_e32 v132, 16, v137
	v_pk_mul_f32 v[74:75], v[74:75], v[130:131]
	v_rcp_f32_e32 v130, v150
	v_rcp_f32_e32 v131, v151
	v_and_b32_e32 v133, 0xffff0000, v137
	v_and_b32_e32 v137, 0xffff0000, v164
	v_and_b32_e32 v139, 0xffff0000, v165
	v_pk_mul_f32 v[130:131], v[130:131], v[132:133]
	v_lshlrev_b32_e32 v132, 16, v142
	v_pk_mul_f32 v[76:77], v[76:77], v[130:131]
	v_and_b32_e32 v131, 0xffff0000, v162
	v_rcp_f32_e32 v130, v1
	v_rcp_f32_e32 v131, v131
	v_and_b32_e32 v133, 0xffff0000, v142
	v_lshlrev_b32_e32 v1, 16, v146
	v_pk_mul_f32 v[130:131], v[130:131], v[132:133]
	s_nop 0
	v_pk_mul_f32 v[102:103], v[102:103], v[130:131]
	v_rcp_f32_e32 v130, v134
	v_rcp_f32_e32 v131, v135
	v_lshlrev_b32_e32 v132, 16, v143
	v_and_b32_e32 v133, 0xffff0000, v143
	v_lshlrev_b32_e32 v134, 16, v147
	v_pk_mul_f32 v[130:131], v[130:131], v[132:133]
	v_lshlrev_b32_e32 v132, 16, v144
	v_pk_mul_f32 v[104:105], v[104:105], v[130:131]
	v_rcp_f32_e32 v130, v136
	v_rcp_f32_e32 v131, v137
	v_and_b32_e32 v133, 0xffff0000, v144
	v_and_b32_e32 v135, 0xffff0000, v147
	v_lshlrev_b32_e32 v136, 16, v148
	v_pk_mul_f32 v[130:131], v[130:131], v[132:133]
	v_lshlrev_b32_e32 v132, 16, v145
	v_pk_mul_f32 v[98:99], v[98:99], v[130:131]
	v_rcp_f32_e32 v130, v138
	v_rcp_f32_e32 v131, v139
	v_and_b32_e32 v133, 0xffff0000, v145
	v_and_b32_e32 v137, 0xffff0000, v148
	v_lshlrev_b32_e32 v138, 16, v149
	v_pk_mul_f32 v[130:131], v[130:131], v[132:133]
	v_lshlrev_b32_e32 v132, 16, v182
	v_pk_mul_f32 v[100:101], v[100:101], v[130:131]
	v_and_b32_e32 v131, 0xffff0000, v146
	v_rcp_f32_e32 v130, v1
	v_rcp_f32_e32 v131, v131
	v_and_b32_e32 v133, 0xffff0000, v182
	v_and_b32_e32 v139, 0xffff0000, v149
	v_pk_mul_f32 v[130:131], v[130:131], v[132:133]
	s_nop 0
	v_pk_mul_f32 v[70:71], v[70:71], v[130:131]
	v_rcp_f32_e32 v130, v134
	v_rcp_f32_e32 v131, v135
	v_lshlrev_b32_e32 v132, 16, v183
	v_and_b32_e32 v133, 0xffff0000, v183
	v_pk_mul_f32 v[130:131], v[130:131], v[132:133]
	s_nop 0
	v_pk_mul_f32 v[72:73], v[72:73], v[130:131]
	v_rcp_f32_e32 v130, v136
	v_rcp_f32_e32 v131, v137
	v_lshlrev_b32_e32 v132, 16, v184
	v_and_b32_e32 v133, 0xffff0000, v184
	v_pk_mul_f32 v[130:131], v[130:131], v[132:133]
	s_nop 0
	v_pk_mul_f32 v[66:67], v[66:67], v[130:131]
	v_rcp_f32_e32 v130, v138
	v_rcp_f32_e32 v131, v139
	v_lshlrev_b32_e32 v132, 16, v185
	v_and_b32_e32 v133, 0xffff0000, v185
	v_pk_mul_f32 v[130:131], v[130:131], v[132:133]
	s_nop 0
	v_pk_mul_f32 v[68:69], v[68:69], v[130:131]
	s_waitcnt vmcnt(0)
;     __device__ __forceinline__ void operator()(f32x4 (&acc)[2][2][4][2], const Unit& u, int wr, int wc, int fr, int fq) const {
;     ...
;         } else if (u.seg < 2) {
;             const bf16_t* gbase = gl + (size_t)u.seg * 8 * 65536;
; #pragma unroll
;             for (int am = 0; am < 4; ++am) { const int ai = am >> 1, mb = (am & 1) * 2;
;                 u32x4 ra[2][2], rb[2][2];
; #pragma unroll
;                 for (int mm = 0; mm < 2; ++mm)
; #pragma unroll
;                     for (int bj = 0; bj < 2; ++bj) { const bf16_t* gp = gbase + ((ai * 4 + mb + mm) * 2 + bj) * 512; ra[mm][bj] = *(const u32x4*)gp; rb[mm][bj] = *(const u32x4*)(gp + 8 * 65536); }
; #pragma unroll
;                 for (int mm = 0; mm < 2; ++mm)
; #pragma unroll
;                     for (int bj = 0; bj < 2; ++bj) { const int m = mb + mm; float ga[8], gb[8]; unpack8(ra[mm][bj], ga); unpack8(rb[mm][bj], gb);
;                         f32x4 v0 = acc[ai][bj][m][0], v1 = acc[ai][bj][m][1];
;                         v0[0] *= ga[0] * __builtin_amdgcn_rcpf(gb[0]); v0[1] *= ga[1] * __builtin_amdgcn_rcpf(gb[1]); v0[2] *= ga[2] * __builtin_amdgcn_rcpf(gb[2]); v0[3] *= ga[3] * __builtin_amdgcn_rcpf(gb[3]);
;                         v1[0] *= ga[4] * __builtin_amdgcn_rcpf(gb[4]); v1[1] *= ga[5] * __builtin_amdgcn_rcpf(gb[5]); v1[2] *= ga[6] * __builtin_amdgcn_rcpf(gb[6]); v1[3] *= ga[7] * __builtin_amdgcn_rcpf(gb[7]);
;                         acc[ai][bj][m][0] = v0; acc[ai][bj][m][1] = v1; }
;             }
	v_mov_b64_e32 v[146:147], v[228:229]
	v_mov_b64_e32 v[148:149], v[230:231]
	v_mov_b64_e32 v[150:151], v[232:233]
	v_mov_b64_e32 v[152:153], v[234:235]
	v_mov_b64_e32 v[138:139], v[236:237]
	v_mov_b64_e32 v[140:141], v[238:239]
	v_mov_b64_e32 v[142:143], v[244:245]
	v_mov_b64_e32 v[144:145], v[246:247]
	v_mov_b64_e32 v[130:131], v[248:249]
	v_mov_b64_e32 v[132:133], v[250:251]
	v_mov_b64_e32 v[134:135], v[198:199]
	v_mov_b64_e32 v[136:137], v[200:201]
	s_nop 0
	v_mov_b64_e32 v[154:155], v[212:213]
	v_mov_b64_e32 v[156:157], v[214:215]
	s_nop 0
	v_mov_b64_e32 v[160:161], v[216:217]
	v_mov_b64_e32 v[162:163], v[218:219]
	s_mov_b32 s98, 0x3000
	s_mov_b32 s99, 0
	v_lshl_add_u64 v[242:243], v[158:159], 0, s[98:99]
	s_mov_b32 s98, 0x103000
	v_lshl_add_u64 v[252:253], v[158:159], 0, s[98:99]
	global_load_dwordx4 v[228:231], v[242:243], off
	global_load_dwordx4 v[232:235], v[252:253], off
	global_load_dwordx4 v[236:239], v[242:243], off offset:1024
	global_load_dwordx4 v[244:247], v[252:253], off offset:1024
	global_load_dwordx4 v[248:251], v[242:243], off offset:2048
	global_load_dwordx4 v[198:201], v[252:253], off offset:2048
	global_load_dwordx4 v[212:215], v[242:243], off offset:3072
	global_load_dwordx4 v[216:219], v[252:253], off offset:3072
	v_lshlrev_b32_e32 v1, 16, v150
	v_and_b32_e32 v164, 0xffff0000, v150
	v_lshlrev_b32_e32 v165, 16, v151
	v_and_b32_e32 v182, 0xffff0000, v151
	v_rcp_f32_e32 v150, v1
	v_rcp_f32_e32 v151, v164
	v_lshlrev_b32_e32 v183, 16, v152
	v_and_b32_e32 v184, 0xffff0000, v152
	v_lshlrev_b32_e32 v185, 16, v153
	v_and_b32_e32 v192, 0xffff0000, v153
	v_lshlrev_b32_e32 v152, 16, v146
	v_and_b32_e32 v153, 0xffff0000, v146
	v_pk_mul_f32 v[150:151], v[150:151], v[152:153]
	v_lshlrev_b32_e32 v146, 16, v147
	v_pk_mul_f32 v[62:63], v[62:63], v[150:151]
	v_rcp_f32_e32 v150, v165
	v_rcp_f32_e32 v151, v182
	v_and_b32_e32 v147, 0xffff0000, v147
	v_lshlrev_b32_e32 v1, 16, v142
	v_and_b32_e32 v152, 0xffff0000, v145
	v_pk_mul_f32 v[146:147], v[150:151], v[146:147]
	v_lshlrev_b32_e32 v150, 16, v148
	v_pk_mul_f32 v[64:65], v[64:65], v[146:147]
	v_rcp_f32_e32 v146, v183
	v_rcp_f32_e32 v147, v184
	v_and_b32_e32 v151, 0xffff0000, v148
	v_lshlrev_b32_e32 v148, 16, v149
	v_and_b32_e32 v149, 0xffff0000, v149
	v_pk_mul_f32 v[146:147], v[146:147], v[150:151]
	v_and_b32_e32 v150, 0xffff0000, v144
	v_pk_mul_f32 v[58:59], v[58:59], v[146:147]
	v_rcp_f32_e32 v146, v185
	v_rcp_f32_e32 v147, v192
	v_lshlrev_b32_e32 v151, 16, v145
	v_and_b32_e32 v145, 0xffff0000, v138
	v_pk_mul_f32 v[146:147], v[146:147], v[148:149]
	s_nop 0
	v_pk_mul_f32 v[60:61], v[60:61], v[146:147]
	v_and_b32_e32 v146, 0xffff0000, v142
	v_lshlrev_b32_e32 v147, 16, v143
	v_and_b32_e32 v148, 0xffff0000, v143
	v_rcp_f32_e32 v142, v1
	v_rcp_f32_e32 v143, v146
	v_lshlrev_b32_e32 v149, 16, v144
	v_lshlrev_b32_e32 v144, 16, v138
	v_lshlrev_b32_e32 v138, 16, v139
	v_pk_mul_f32 v[142:143], v[142:143], v[144:145]
	v_and_b32_e32 v139, 0xffff0000, v139
	v_pk_mul_f32 v[30:31], v[30:31], v[142:143]
	v_rcp_f32_e32 v142, v147
	v_rcp_f32_e32 v143, v148
	v_lshlrev_b32_e32 v1, 16, v134
	v_and_b32_e32 v144, 0xffff0000, v137
	v_pk_mul_f32 v[138:139], v[142:143], v[138:139]
	s_nop 0
	v_pk_mul_f32 v[32:33], v[32:33], v[138:139]
	v_rcp_f32_e32 v138, v149
	v_rcp_f32_e32 v139, v150
	v_lshlrev_b32_e32 v142, 16, v140
	v_and_b32_e32 v143, 0xffff0000, v140
	v_lshlrev_b32_e32 v140, 16, v141
	v_pk_mul_f32 v[138:139], v[138:139], v[142:143]
	v_and_b32_e32 v141, 0xffff0000, v141
	v_pk_mul_f32 v[26:27], v[26:27], v[138:139]
	v_rcp_f32_e32 v138, v151
	v_rcp_f32_e32 v139, v152
	v_and_b32_e32 v142, 0xffff0000, v136
	v_lshlrev_b32_e32 v143, 16, v137
	v_and_b32_e32 v137, 0xffff0000, v130
	v_pk_mul_f32 v[138:139], v[138:139], v[140:141]
	v_and_b32_e32 v140, 0xffff0000, v135
	v_pk_mul_f32 v[28:29], v[28:29], v[138:139]
	v_and_b32_e32 v138, 0xffff0000, v134
	v_lshlrev_b32_e32 v139, 16, v135
	v_rcp_f32_e32 v134, v1
	v_rcp_f32_e32 v135, v138
	v_lshlrev_b32_e32 v141, 16, v136
	v_lshlrev_b32_e32 v136, 16, v130
	v_lshlrev_b32_e32 v130, 16, v131
	v_pk_mul_f32 v[134:135], v[134:135], v[136:137]
	v_and_b32_e32 v131, 0xffff0000, v131
	v_pk_mul_f32 v[54:55], v[54:55], v[134:135]
	v_rcp_f32_e32 v134, v139
	v_rcp_f32_e32 v135, v140
	v_lshlrev_b32_e32 v1, 16, v160
	v_lshlrev_b32_e32 v136, 16, v162
	v_and_b32_e32 v137, 0xffff0000, v162
	v_pk_mul_f32 v[130:131], v[134:135], v[130:131]
	v_lshlrev_b32_e32 v134, 16, v132
	v_pk_mul_f32 v[56:57], v[56:57], v[130:131]
	v_rcp_f32_e32 v130, v141
	v_rcp_f32_e32 v131, v142
	v_and_b32_e32 v135, 0xffff0000, v132
	v_lshlrev_b32_e32 v132, 16, v133
	v_and_b32_e32 v133, 0xffff0000, v133
	v_pk_mul_f32 v[130:131], v[130:131], v[134:135]
	v_lshlrev_b32_e32 v134, 16, v161
	v_pk_mul_f32 v[50:51], v[50:51], v[130:131]
	v_rcp_f32_e32 v130, v143
	v_rcp_f32_e32 v131, v144
	v_and_b32_e32 v135, 0xffff0000, v161
	v_lshlrev_b32_e32 v138, 16, v163
	v_and_b32_e32 v139, 0xffff0000, v163
	v_pk_mul_f32 v[130:131], v[130:131], v[132:133]
	v_lshlrev_b32_e32 v132, 16, v154
	v_pk_mul_f32 v[52:53], v[52:53], v[130:131]
	v_and_b32_e32 v131, 0xffff0000, v160
	v_rcp_f32_e32 v130, v1
	v_rcp_f32_e32 v131, v131
	v_and_b32_e32 v133, 0xffff0000, v154
	v_add_co_u32_e32 v142, vcc, s1, v158
	v_pk_mul_f32 v[130:131], v[130:131], v[132:133]
	v_lshlrev_b32_e32 v132, 16, v155
	v_pk_mul_f32 v[22:23], v[22:23], v[130:131]
	v_rcp_f32_e32 v130, v134
	v_rcp_f32_e32 v131, v135
	v_and_b32_e32 v133, 0xffff0000, v155
	v_addc_co_u32_e32 v143, vcc, 0, v159, vcc
	v_pk_mul_f32 v[130:131], v[130:131], v[132:133]
	v_lshlrev_b32_e32 v132, 16, v156
	v_pk_mul_f32 v[24:25], v[24:25], v[130:131]
	v_rcp_f32_e32 v130, v136
	v_rcp_f32_e32 v131, v137
	v_and_b32_e32 v133, 0xffff0000, v156
	s_mov_b32 s1, 0x103000
	v_add_co_u32_e32 v154, vcc, s1, v158
	v_pk_mul_f32 v[130:131], v[130:131], v[132:133]
	v_lshlrev_b32_e32 v132, 16, v157
	v_pk_mul_f32 v[18:19], v[18:19], v[130:131]
	v_rcp_f32_e32 v130, v138
	v_rcp_f32_e32 v131, v139
	v_and_b32_e32 v133, 0xffff0000, v157
	v_addc_co_u32_e32 v155, vcc, 0, v159, vcc
	v_pk_mul_f32 v[130:131], v[130:131], v[132:133]
	s_nop 0
	v_pk_mul_f32 v[20:21], v[20:21], v[130:131]
	s_waitcnt vmcnt(0)
;     __device__ __forceinline__ void operator()(f32x4 (&acc)[2][2][4][2], const Unit& u, int wr, int wc, int fr, int fq) const {
;     ...
;         } else if (u.seg < 2) {
;             const bf16_t* gbase = gl + (size_t)u.seg * 8 * 65536;
; #pragma unroll
;             for (int am = 0; am < 4; ++am) { const int ai = am >> 1, mb = (am & 1) * 2;
;                 u32x4 ra[2][2], rb[2][2];
; #pragma unroll
;                 for (int mm = 0; mm < 2; ++mm)
; #pragma unroll
;                     for (int bj = 0; bj < 2; ++bj) { const bf16_t* gp = gbase + ((ai * 4 + mb + mm) * 2 + bj) * 512; ra[mm][bj] = *(const u32x4*)gp; rb[mm][bj] = *(const u32x4*)(gp + 8 * 65536); }
; #pragma unroll
;                 for (int mm = 0; mm < 2; ++mm)
; #pragma unroll
;                     for (int bj = 0; bj < 2; ++bj) { const int m = mb + mm; float ga[8], gb[8]; unpack8(ra[mm][bj], ga); unpack8(rb[mm][bj], gb);
;                         f32x4 v0 = acc[ai][bj][m][0], v1 = acc[ai][bj][m][1];
;                         v0[0] *= ga[0] * __builtin_amdgcn_rcpf(gb[0]); v0[1] *= ga[1] * __builtin_amdgcn_rcpf(gb[1]); v0[2] *= ga[2] * __builtin_amdgcn_rcpf(gb[2]); v0[3] *= ga[3] * __builtin_amdgcn_rcpf(gb[3]);
;                         v1[0] *= ga[4] * __builtin_amdgcn_rcpf(gb[4]); v1[1] *= ga[5] * __builtin_amdgcn_rcpf(gb[5]); v1[2] *= ga[6] * __builtin_amdgcn_rcpf(gb[6]); v1[3] *= ga[7] * __builtin_amdgcn_rcpf(gb[7]);
;                         acc[ai][bj][m][0] = v0; acc[ai][bj][m][1] = v1; }
;             }
	v_mov_b64_e32 v[130:131], v[228:229]
	v_mov_b64_e32 v[132:133], v[230:231]
	v_mov_b64_e32 v[146:147], v[232:233]
	v_mov_b64_e32 v[148:149], v[234:235]
	v_mov_b64_e32 v[134:135], v[236:237]
	v_mov_b64_e32 v[136:137], v[238:239]
	v_mov_b64_e32 v[150:151], v[244:245]
	v_mov_b64_e32 v[152:153], v[246:247]
	v_mov_b64_e32 v[138:139], v[248:249]
	v_mov_b64_e32 v[140:141], v[250:251]
	v_mov_b64_e32 v[158:159], v[198:199]
	v_mov_b64_e32 v[160:161], v[200:201]
	s_nop 0
	v_mov_b64_e32 v[142:143], v[212:213]
	v_mov_b64_e32 v[144:145], v[214:215]
	s_nop 0
	v_mov_b64_e32 v[154:155], v[216:217]
	v_mov_b64_e32 v[156:157], v[218:219]
	s_nop 0
	v_lshlrev_b32_e32 v1, 16, v146
	v_and_b32_e32 v162, 0xffff0000, v146
	v_lshlrev_b32_e32 v163, 16, v147
	v_and_b32_e32 v164, 0xffff0000, v147
	v_rcp_f32_e32 v146, v1
	v_rcp_f32_e32 v147, v162
	v_lshlrev_b32_e32 v165, 16, v148
	v_and_b32_e32 v182, 0xffff0000, v148
	v_lshlrev_b32_e32 v183, 16, v149
	v_and_b32_e32 v184, 0xffff0000, v149
	v_lshlrev_b32_e32 v148, 16, v130
	v_and_b32_e32 v149, 0xffff0000, v130
	v_pk_mul_f32 v[146:147], v[146:147], v[148:149]
	v_lshlrev_b32_e32 v130, 16, v131
	v_pk_mul_f32 v[46:47], v[46:47], v[146:147]
	v_rcp_f32_e32 v146, v163
	v_rcp_f32_e32 v147, v164
	v_and_b32_e32 v131, 0xffff0000, v131
	v_lshlrev_b32_e32 v1, 16, v150
	v_lshlrev_b32_e32 v148, 16, v152
	v_pk_mul_f32 v[130:131], v[146:147], v[130:131]
	v_lshlrev_b32_e32 v146, 16, v132
	v_pk_mul_f32 v[48:49], v[48:49], v[130:131]
	v_rcp_f32_e32 v130, v165
	v_rcp_f32_e32 v131, v182
	v_and_b32_e32 v147, 0xffff0000, v132
	v_lshlrev_b32_e32 v132, 16, v133
	v_and_b32_e32 v133, 0xffff0000, v133
	v_pk_mul_f32 v[130:131], v[130:131], v[146:147]
	v_lshlrev_b32_e32 v146, 16, v151
	v_pk_mul_f32 v[42:43], v[42:43], v[130:131]
	v_rcp_f32_e32 v130, v183
	v_rcp_f32_e32 v131, v184
	v_and_b32_e32 v147, 0xffff0000, v151
	v_and_b32_e32 v149, 0xffff0000, v152
	v_and_b32_e32 v151, 0xffff0000, v153
	v_pk_mul_f32 v[130:131], v[130:131], v[132:133]
	v_lshlrev_b32_e32 v132, 16, v134
	v_pk_mul_f32 v[44:45], v[44:45], v[130:131]
	v_and_b32_e32 v131, 0xffff0000, v150
	v_rcp_f32_e32 v130, v1
	v_rcp_f32_e32 v131, v131
	v_and_b32_e32 v133, 0xffff0000, v134
	v_lshlrev_b32_e32 v150, 16, v153
	v_lshlrev_b32_e32 v1, 16, v158
	v_pk_mul_f32 v[130:131], v[130:131], v[132:133]
	v_lshlrev_b32_e32 v132, 16, v135
	v_pk_mul_f32 v[14:15], v[14:15], v[130:131]
	v_rcp_f32_e32 v130, v146
	v_rcp_f32_e32 v131, v147
	v_and_b32_e32 v133, 0xffff0000, v135
	v_lshlrev_b32_e32 v134, 16, v159
	v_and_b32_e32 v135, 0xffff0000, v159
	v_pk_mul_f32 v[130:131], v[130:131], v[132:133]
	v_lshlrev_b32_e32 v132, 16, v136
	v_pk_mul_f32 v[16:17], v[16:17], v[130:131]
	v_rcp_f32_e32 v130, v148
	v_rcp_f32_e32 v131, v149
	v_and_b32_e32 v133, 0xffff0000, v136
	v_lshlrev_b32_e32 v136, 16, v160
	v_lshlrev_b32_e32 v146, 16, v161
	v_pk_mul_f32 v[130:131], v[130:131], v[132:133]
	v_lshlrev_b32_e32 v132, 16, v137
	v_pk_mul_f32 v[10:11], v[10:11], v[130:131]
	v_rcp_f32_e32 v130, v150
	v_rcp_f32_e32 v131, v151
	v_and_b32_e32 v133, 0xffff0000, v137
	v_and_b32_e32 v137, 0xffff0000, v160
	v_and_b32_e32 v147, 0xffff0000, v161
	v_pk_mul_f32 v[130:131], v[130:131], v[132:133]
	v_lshlrev_b32_e32 v132, 16, v138
	v_pk_mul_f32 v[12:13], v[12:13], v[130:131]
	v_and_b32_e32 v131, 0xffff0000, v158
	v_rcp_f32_e32 v130, v1
	v_rcp_f32_e32 v131, v131
	v_and_b32_e32 v133, 0xffff0000, v138
	v_lshlrev_b32_e32 v1, 16, v154
	v_lshlrev_b32_e32 v138, 16, v157
	v_pk_mul_f32 v[130:131], v[130:131], v[132:133]
	v_lshlrev_b32_e32 v132, 16, v139
	v_pk_mul_f32 v[38:39], v[38:39], v[130:131]
	v_rcp_f32_e32 v130, v134
	v_rcp_f32_e32 v131, v135
	v_and_b32_e32 v133, 0xffff0000, v139
	v_lshlrev_b32_e32 v134, 16, v155
	v_and_b32_e32 v135, 0xffff0000, v155
	v_pk_mul_f32 v[130:131], v[130:131], v[132:133]
	v_lshlrev_b32_e32 v132, 16, v140
	v_pk_mul_f32 v[40:41], v[40:41], v[130:131]
	v_rcp_f32_e32 v130, v136
	v_rcp_f32_e32 v131, v137
	v_and_b32_e32 v133, 0xffff0000, v140
	v_lshlrev_b32_e32 v136, 16, v156
	v_and_b32_e32 v137, 0xffff0000, v156
	v_pk_mul_f32 v[130:131], v[130:131], v[132:133]
	v_lshlrev_b32_e32 v132, 16, v141
	v_pk_mul_f32 v[34:35], v[34:35], v[130:131]
	v_rcp_f32_e32 v130, v146
	v_rcp_f32_e32 v131, v147
	v_and_b32_e32 v133, 0xffff0000, v141
	v_and_b32_e32 v139, 0xffff0000, v157
	v_pk_mul_f32 v[130:131], v[130:131], v[132:133]
	s_nop 0
	v_pk_mul_f32 v[36:37], v[36:37], v[130:131]
	v_and_b32_e32 v131, 0xffff0000, v154
	v_rcp_f32_e32 v130, v1
	v_rcp_f32_e32 v131, v131
	v_lshlrev_b32_e32 v132, 16, v142
	v_and_b32_e32 v133, 0xffff0000, v142
	v_pk_mul_f32 v[130:131], v[130:131], v[132:133]
	s_nop 0
	v_pk_mul_f32 v[6:7], v[6:7], v[130:131]
	v_rcp_f32_e32 v130, v134
	v_rcp_f32_e32 v131, v135
	v_lshlrev_b32_e32 v132, 16, v143
	v_and_b32_e32 v133, 0xffff0000, v143
	v_pk_mul_f32 v[130:131], v[130:131], v[132:133]
	s_nop 0
	v_pk_mul_f32 v[8:9], v[8:9], v[130:131]
	v_rcp_f32_e32 v130, v136
	v_rcp_f32_e32 v131, v137
	v_lshlrev_b32_e32 v132, 16, v144
	v_and_b32_e32 v133, 0xffff0000, v144
	v_pk_mul_f32 v[130:131], v[130:131], v[132:133]
	s_nop 0
	v_pk_mul_f32 v[2:3], v[2:3], v[130:131]
	v_rcp_f32_e32 v130, v138
	v_rcp_f32_e32 v131, v139
	v_lshlrev_b32_e32 v132, 16, v145
	v_and_b32_e32 v133, 0xffff0000, v145
	v_pk_mul_f32 v[130:131], v[130:131], v[132:133]
	s_nop 0
	v_pk_mul_f32 v[4:5], v[4:5], v[130:131]
